# PN: in-projection epilogue stores the bf16 proj tile with the nt (streaming) policy (consumed by other CUs next phase)
# baseline (speedup 1.0000x reference)
.LBB0_326:
	s_andn2_b64 vcc, exec, s[28:29]
	s_cbranch_vccnz .LBB0_317
	v_readlane_b32 s6, v253, 59
	v_lshl_or_b32 v148, s87, 8, v144
	v_readlane_b32 s7, v253, 60
	v_ashrrev_i32_e32 v149, 31, v148
	s_movk_i32 s5, 0x3800
	v_mov_b64_e32 v[150:151], s[6:7]
	v_cvt_pk_bf16_f32 v68, v68, v69
	v_cvt_pk_bf16_f32 v69, v70, v71
	v_cvt_pk_bf16_f32 v70, v64, v65
	v_add_u32_e32 v64, 0x80, v146
	v_mad_i64_i32 v[152:153], s[6:7], v146, s5, v[150:151]
	v_lshlrev_b64 v[148:149], 1, v[148:149]
	v_cvt_pk_bf16_f32 v108, v108, v109
	v_cvt_pk_bf16_f32 v109, v110, v111
	v_cvt_pk_bf16_f32 v110, v104, v105
	v_or_b32_e32 v104, 16, v146
	v_mad_i64_i32 v[64:65], s[6:7], v64, s5, v[150:151]
	v_cvt_pk_bf16_f32 v44, v44, v45
	v_cvt_pk_bf16_f32 v45, v46, v47
	v_cvt_pk_bf16_f32 v46, v40, v41
	v_add_u32_e32 v40, 0x90, v146
	v_lshl_add_u64 v[152:153], v[152:153], 0, v[148:149]
	v_cvt_pk_bf16_f32 v111, v106, v107
	v_mad_i64_i32 v[104:105], s[6:7], v104, s5, v[150:151]
	v_cvt_pk_bf16_f32 v92, v92, v93
	v_cvt_pk_bf16_f32 v93, v94, v95
	v_cvt_pk_bf16_f32 v94, v88, v89
	v_or_b32_e32 v88, 32, v146
	v_lshl_add_u64 v[64:65], v[64:65], 0, v[148:149]
	v_cvt_pk_bf16_f32 v47, v42, v43
	v_mad_i64_i32 v[40:41], s[6:7], v40, s5, v[150:151]
	v_cvt_pk_bf16_f32 v28, v28, v29
	v_cvt_pk_bf16_f32 v29, v30, v31
	v_cvt_pk_bf16_f32 v30, v24, v25
	v_add_u32_e32 v24, 0xa0, v146
	global_store_dwordx4 v[152:153], v[108:111], off offset:256 nt
	v_cvt_pk_bf16_f32 v95, v90, v91
	v_mad_i64_i32 v[88:89], s[6:7], v88, s5, v[150:151]
	v_lshl_add_u64 v[108:109], v[104:105], 0, v[148:149]
	v_cvt_pk_bf16_f32 v76, v76, v77
	v_cvt_pk_bf16_f32 v77, v78, v79
	v_cvt_pk_bf16_f32 v78, v72, v73
	v_or_b32_e32 v72, 48, v146
	global_store_dwordx4 v[64:65], v[44:47], off offset:256 nt
	v_cvt_pk_bf16_f32 v31, v26, v27
	v_mad_i64_i32 v[24:25], s[6:7], v24, s5, v[150:151]
	v_lshl_add_u64 v[44:45], v[40:41], 0, v[148:149]
	v_cvt_pk_bf16_f32 v12, v12, v13
	v_cvt_pk_bf16_f32 v13, v14, v15
	v_cvt_pk_bf16_f32 v14, v8, v9
	v_add_u32_e32 v8, 0xb0, v146
	global_store_dwordx4 v[108:109], v[92:95], off offset:256 nt
	v_cvt_pk_bf16_f32 v79, v74, v75
	v_mad_i64_i32 v[72:73], s[6:7], v72, s5, v[150:151]
	v_lshl_add_u64 v[92:93], v[88:89], 0, v[148:149]
	global_store_dwordx4 v[44:45], v[28:31], off offset:256 nt
	v_cvt_pk_bf16_f32 v15, v10, v11
	v_mad_i64_i32 v[8:9], s[6:7], v8, s5, v[150:151]
	v_lshl_add_u64 v[28:29], v[24:25], 0, v[148:149]
	v_cvt_pk_bf16_f32 v124, v124, v125
	v_cvt_pk_bf16_f32 v125, v126, v127
	v_cvt_pk_bf16_f32 v126, v120, v121
	v_cvt_pk_bf16_f32 v127, v122, v123
	v_cvt_pk_bf16_f32 v104, v116, v117
	v_cvt_pk_bf16_f32 v105, v118, v119
	v_cvt_pk_bf16_f32 v106, v112, v113
	v_cvt_pk_bf16_f32 v107, v114, v115
	v_cvt_pk_bf16_f32 v88, v100, v101
	v_cvt_pk_bf16_f32 v89, v102, v103
	v_cvt_pk_bf16_f32 v90, v96, v97
	v_cvt_pk_bf16_f32 v91, v98, v99
	global_store_dwordx4 v[92:93], v[76:79], off offset:256 nt
	v_cvt_pk_bf16_f32 v74, v80, v81
	v_cvt_pk_bf16_f32 v75, v82, v83
	v_lshl_add_u64 v[76:77], v[72:73], 0, v[148:149]
	v_cvt_pk_bf16_f32 v72, v84, v85
	v_cvt_pk_bf16_f32 v73, v86, v87
	v_cvt_pk_bf16_f32 v71, v66, v67
	v_cvt_pk_bf16_f32 v60, v60, v61
	v_cvt_pk_bf16_f32 v61, v62, v63
	v_cvt_pk_bf16_f32 v62, v56, v57
	v_cvt_pk_bf16_f32 v63, v58, v59
	v_cvt_pk_bf16_f32 v40, v52, v53
	v_cvt_pk_bf16_f32 v41, v54, v55
	v_cvt_pk_bf16_f32 v42, v48, v49
	v_cvt_pk_bf16_f32 v43, v50, v51
	v_cvt_pk_bf16_f32 v24, v36, v37
	v_cvt_pk_bf16_f32 v25, v38, v39
	v_cvt_pk_bf16_f32 v26, v32, v33
	v_cvt_pk_bf16_f32 v27, v34, v35
	global_store_dwordx4 v[28:29], v[12:15], off offset:256 nt
	v_cvt_pk_bf16_f32 v10, v16, v17
	v_cvt_pk_bf16_f32 v11, v18, v19
	v_lshl_add_u64 v[12:13], v[8:9], 0, v[148:149]
	v_cvt_pk_bf16_f32 v8, v20, v21
	v_cvt_pk_bf16_f32 v9, v22, v23
	v_cvt_pk_bf16_f32 v4, v4, v5
	v_cvt_pk_bf16_f32 v5, v6, v7
	v_cvt_pk_bf16_f32 v6, v0, v1
	v_cvt_pk_bf16_f32 v7, v2, v3
	global_store_dwordx4 v[152:153], v[124:127], off nt
	global_store_dwordx4 v[108:109], v[104:107], off nt
	global_store_dwordx4 v[92:93], v[88:91], off nt
	global_store_dwordx4 v[76:77], v[72:75], off nt
	global_store_dwordx4 v[76:77], v[68:71], off offset:256 nt
	global_store_dwordx4 v[64:65], v[60:63], off nt
	global_store_dwordx4 v[44:45], v[40:43], off nt
	global_store_dwordx4 v[28:29], v[24:27], off nt
	global_store_dwordx4 v[12:13], v[8:11], off nt
	global_store_dwordx4 v[12:13], v[4:7], off offset:256 nt
	s_branch .LBB0_317
